# gate tile epilogue rewritten by hand: lnx_g/b loaded once per tile, next row group's Y/V/RK loads kept in flight
# speedup vs baseline: 1.0016x; 1.0016x over previous
.LBB0_1251:
	s_waitcnt lgkmcnt(0)
	v_lshl_or_b32 v156, s20, 7, v170
	v_add_u32_e32 v154, s19, v156
	s_lshl_b32 s0, s18, 6
	v_cmp_gt_i32_e32 vcc, s14, v154
	s_or_b32 s18, s0, s6
	v_mov_b64_e32 v[132:133], s[88:89]
	v_cndmask_b32_e32 v130, v168, v154, vcc
	v_mad_i64_i32 v[132:133], s[0:1], v130, s15, v[132:133]
	s_lshl_b32 s6, s18, 1
	s_waitcnt vmcnt(0)
	v_lshl_add_u64 v[132:133], v[132:133], 0, s[6:7]
	v_lshlrev_b32_e32 v0, 3, v169
	s_waitcnt lgkmcnt(0)
	s_barrier
	v_readlane_b32 s36, v192, 0
	v_readlane_b32 s37, v192, 1
	v_lshlrev_b32_e32 v0, 2, v169
	v_or_b32_e32 v0, s18, v0
	v_lshlrev_b32_e32 v254, 1, v0
	v_lshlrev_b32_e32 v0, 2, v0
	global_load_dwordx4 v[194:197], v0, s[26:27] offset:0
	global_load_dwordx4 v[198:201], v0, s[26:27] offset:64
	global_load_dwordx4 v[202:205], v0, s[26:27] offset:128
	global_load_dwordx4 v[206:209], v0, s[26:27] offset:192
	global_load_dwordx4 v[210:213], v0, s[36:37] offset:0
	global_load_dwordx4 v[214:217], v0, s[36:37] offset:64
	global_load_dwordx4 v[218:221], v0, s[36:37] offset:128
	global_load_dwordx4 v[222:225], v0, s[36:37] offset:192
	v_xor_b32_e32 v255, 16, v167
	v_lshlrev_b32_e32 v255, 2, v255
	v_xor_b32_e32 v193, 32, v167
	v_lshlrev_b32_e32 v193, 2, v193
	v_mov_b32_e32 v0, v156
	s_lshr_b32 s20, s18, 4
	s_mov_b32 s21, 0
	s_add_i32 s0, s19, 0
	v_add_u32_e32 v253, s0, v0
	v_cmp_gt_i32_e32 vcc, s14, v253
	s_nop 1
	v_cndmask_b32_e32 v253, v168, v253, vcc
	v_mov_b64_e32 v[148:149], s[88:89]
	v_mad_i64_i32 v[148:149], s[0:1], v253, s15, v[148:149]
	v_mov_b32_e32 v244, v254
	v_mov_b32_e32 v245, 0
	v_lshl_add_u64 v[148:149], v[148:149], 0, v[244:245]
	global_load_dwordx2 v[130:131], v[148:149], off offset:0
	global_load_dwordx2 v[132:133], v[148:149], off offset:32
	global_load_dwordx2 v[134:135], v[148:149], off offset:64
	global_load_dwordx2 v[136:137], v[148:149], off offset:96
	v_ashrrev_i32_e32 v251, 31, v253
	v_mov_b32_e32 v250, v253
	v_lshlrev_b64 v[246:247], 11, v[250:251]
	v_lshl_add_u64 v[246:247], s[54:55], 0, v[246:247]
	v_lshl_add_u64 v[246:247], v[246:247], 0, v[244:245]
	global_load_dwordx2 v[138:139], v[246:247], off offset:0
	global_load_dwordx2 v[140:141], v[246:247], off offset:32
	global_load_dwordx2 v[142:143], v[246:247], off offset:64
	global_load_dwordx2 v[144:145], v[246:247], off offset:96
	v_lshlrev_b64 v[246:247], 6, v[250:251]
	v_lshl_add_u64 v[246:247], s[58:59], 0, v[246:247]
	v_lshl_add_u64 v[246:247], v[246:247], 0, s[20:21]
	global_load_dword v146, v[246:247], off
	s_add_i32 s0, s19, 16
	v_add_u32_e32 v253, s0, v0
	v_cmp_gt_i32_e32 vcc, s14, v253
	s_nop 1
	v_cndmask_b32_e32 v253, v168, v253, vcc
	v_mov_b64_e32 v[226:227], s[88:89]
	v_mad_i64_i32 v[226:227], s[0:1], v253, s15, v[226:227]
	v_mov_b32_e32 v244, v254
	v_mov_b32_e32 v245, 0
	v_lshl_add_u64 v[226:227], v[226:227], 0, v[244:245]
	global_load_dwordx2 v[150:151], v[226:227], off offset:0
	global_load_dwordx2 v[152:153], v[226:227], off offset:32
	global_load_dwordx2 v[154:155], v[226:227], off offset:64
	global_load_dwordx2 v[156:157], v[226:227], off offset:96
	v_ashrrev_i32_e32 v251, 31, v253
	v_mov_b32_e32 v250, v253
	v_lshlrev_b64 v[246:247], 11, v[250:251]
	v_lshl_add_u64 v[246:247], s[54:55], 0, v[246:247]
	v_lshl_add_u64 v[246:247], v[246:247], 0, v[244:245]
	global_load_dwordx2 v[158:159], v[246:247], off offset:0
	global_load_dwordx2 v[160:161], v[246:247], off offset:32
	global_load_dwordx2 v[162:163], v[246:247], off offset:64
	global_load_dwordx2 v[164:165], v[246:247], off offset:96
	v_lshlrev_b64 v[246:247], 6, v[250:251]
	v_lshl_add_u64 v[246:247], s[58:59], 0, v[246:247]
	v_lshl_add_u64 v[246:247], v[246:247], 0, s[20:21]
	global_load_dword v147, v[246:247], off
	s_waitcnt vmcnt(9)
	v_lshlrev_b32_e32 v228, 16, v130
	v_and_b32_e32 v229, 0xffff0000, v130
	v_lshlrev_b32_e32 v230, 16, v131
	v_and_b32_e32 v231, 0xffff0000, v131
	v_lshlrev_b32_e32 v232, 16, v132
	v_and_b32_e32 v233, 0xffff0000, v132
	v_lshlrev_b32_e32 v234, 16, v133
	v_and_b32_e32 v235, 0xffff0000, v133
	v_lshlrev_b32_e32 v236, 16, v134
	v_and_b32_e32 v237, 0xffff0000, v134
	v_lshlrev_b32_e32 v238, 16, v135
	v_and_b32_e32 v239, 0xffff0000, v135
	v_lshlrev_b32_e32 v240, 16, v136
	v_and_b32_e32 v241, 0xffff0000, v136
	v_lshlrev_b32_e32 v242, 16, v137
	v_and_b32_e32 v243, 0xffff0000, v137
	v_add_f32_e32 v250, v228, v229
	v_add_f32_e32 v251, v230, v231
	v_add_f32_e32 v250, v250, v232
	v_add_f32_e32 v251, v251, v233
	v_add_f32_e32 v250, v250, v234
	v_add_f32_e32 v251, v251, v235
	v_add_f32_e32 v250, v250, v236
	v_add_f32_e32 v251, v251, v237
	v_add_f32_e32 v250, v250, v238
	v_add_f32_e32 v251, v251, v239
	v_add_f32_e32 v250, v250, v240
	v_add_f32_e32 v251, v251, v241
	v_add_f32_e32 v250, v250, v242
	v_add_f32_e32 v251, v251, v243
	v_add_f32_e32 v250, v250, v251
	ds_bpermute_b32 v251, v255, v250
	s_waitcnt lgkmcnt(0)
	v_add_f32_e32 v250, v250, v251
	ds_bpermute_b32 v251, v193, v250
	s_waitcnt lgkmcnt(0)
	v_add_f32_e32 v250, v250, v251
	v_fmac_f32_e32 v228, 0xbc800000, v250
	v_fmac_f32_e32 v229, 0xbc800000, v250
	v_fmac_f32_e32 v230, 0xbc800000, v250
	v_fmac_f32_e32 v231, 0xbc800000, v250
	v_fmac_f32_e32 v232, 0xbc800000, v250
	v_fmac_f32_e32 v233, 0xbc800000, v250
	v_fmac_f32_e32 v234, 0xbc800000, v250
	v_fmac_f32_e32 v235, 0xbc800000, v250
	v_fmac_f32_e32 v236, 0xbc800000, v250
	v_fmac_f32_e32 v237, 0xbc800000, v250
	v_fmac_f32_e32 v238, 0xbc800000, v250
	v_fmac_f32_e32 v239, 0xbc800000, v250
	v_fmac_f32_e32 v240, 0xbc800000, v250
	v_fmac_f32_e32 v241, 0xbc800000, v250
	v_fmac_f32_e32 v242, 0xbc800000, v250
	v_fmac_f32_e32 v243, 0xbc800000, v250
	v_mul_f32_e32 v250, v228, v228
	v_mul_f32_e32 v251, v229, v229
	v_fmac_f32_e32 v250, v230, v230
	v_fmac_f32_e32 v251, v231, v231
	v_fmac_f32_e32 v250, v232, v232
	v_fmac_f32_e32 v251, v233, v233
	v_fmac_f32_e32 v250, v234, v234
	v_fmac_f32_e32 v251, v235, v235
	v_fmac_f32_e32 v250, v236, v236
	v_fmac_f32_e32 v251, v237, v237
	v_fmac_f32_e32 v250, v238, v238
	v_fmac_f32_e32 v251, v239, v239
	v_fmac_f32_e32 v250, v240, v240
	v_fmac_f32_e32 v251, v241, v241
	v_fmac_f32_e32 v250, v242, v242
	v_fmac_f32_e32 v251, v243, v243
	v_add_f32_e32 v250, v250, v251
	ds_bpermute_b32 v251, v255, v250
	s_waitcnt lgkmcnt(0)
	v_add_f32_e32 v250, v250, v251
	ds_bpermute_b32 v251, v193, v250
	s_waitcnt lgkmcnt(0)
	v_add_f32_e32 v250, v250, v251
	v_fmamk_f32 v250, v250, 0x3c800000, v166
	v_mul_f32_e32 v251, 0x4b800000, v250
	v_cmp_gt_f32_e64 s[0:1], s16, v250
	s_nop 1
	v_cndmask_b32_e64 v250, v250, v251, s[0:1]
	v_rsq_f32_e32 v252, v250
	s_nop 0
	v_mul_f32_e32 v251, 0x45800000, v252
	v_cndmask_b32_e64 v252, v252, v251, s[0:1]
	v_mul_f32_e32 v228, v228, v252
	v_fma_f32 v228, v228, v194, v210
	v_lshlrev_b32_e32 v244, 16, v138
	v_fmac_f32_e32 v228, v146, v244
	v_mul_f32_e32 v228, v126, v228
	v_mul_f32_e32 v229, v229, v252
	v_fma_f32 v229, v229, v195, v211
	v_and_b32_e32 v244, 0xffff0000, v138
	v_fmac_f32_e32 v229, v146, v244
	v_mul_f32_e32 v229, v127, v229
	v_mul_f32_e32 v230, v230, v252
	v_fma_f32 v230, v230, v196, v212
	v_lshlrev_b32_e32 v244, 16, v139
	v_fmac_f32_e32 v230, v146, v244
	v_mul_f32_e32 v230, v128, v230
	v_mul_f32_e32 v231, v231, v252
	v_fma_f32 v231, v231, v197, v213
	v_and_b32_e32 v244, 0xffff0000, v139
	v_fmac_f32_e32 v231, v146, v244
	v_mul_f32_e32 v231, v129, v231
	v_cvt_pk_bf16_f32 v228, v228, v229
	v_cvt_pk_bf16_f32 v229, v230, v231
	v_mul_f32_e32 v232, v232, v252
	v_fma_f32 v232, v232, v198, v214
	v_lshlrev_b32_e32 v244, 16, v140
	v_fmac_f32_e32 v232, v146, v244
	v_mul_f32_e32 v232, v122, v232
	v_mul_f32_e32 v233, v233, v252
	v_fma_f32 v233, v233, v199, v215
	v_and_b32_e32 v244, 0xffff0000, v140
	v_fmac_f32_e32 v233, v146, v244
	v_mul_f32_e32 v233, v123, v233
	v_mul_f32_e32 v234, v234, v252
	v_fma_f32 v234, v234, v200, v216
	v_lshlrev_b32_e32 v244, 16, v141
	v_fmac_f32_e32 v234, v146, v244
	v_mul_f32_e32 v234, v124, v234
	v_mul_f32_e32 v235, v235, v252
	v_fma_f32 v235, v235, v201, v217
	v_and_b32_e32 v244, 0xffff0000, v141
	v_fmac_f32_e32 v235, v146, v244
	v_mul_f32_e32 v235, v125, v235
	v_cvt_pk_bf16_f32 v232, v232, v233
	v_cvt_pk_bf16_f32 v233, v234, v235
	v_mul_f32_e32 v236, v236, v252
	v_fma_f32 v236, v236, v202, v218
	v_lshlrev_b32_e32 v244, 16, v142
	v_fmac_f32_e32 v236, v146, v244
	v_mul_f32_e32 v236, v118, v236
	v_mul_f32_e32 v237, v237, v252
	v_fma_f32 v237, v237, v203, v219
	v_and_b32_e32 v244, 0xffff0000, v142
	v_fmac_f32_e32 v237, v146, v244
	v_mul_f32_e32 v237, v119, v237
	v_mul_f32_e32 v238, v238, v252
	v_fma_f32 v238, v238, v204, v220
	v_lshlrev_b32_e32 v244, 16, v143
	v_fmac_f32_e32 v238, v146, v244
	v_mul_f32_e32 v238, v120, v238
	v_mul_f32_e32 v239, v239, v252
	v_fma_f32 v239, v239, v205, v221
	v_and_b32_e32 v244, 0xffff0000, v143
	v_fmac_f32_e32 v239, v146, v244
	v_mul_f32_e32 v239, v121, v239
	v_cvt_pk_bf16_f32 v236, v236, v237
	v_cvt_pk_bf16_f32 v237, v238, v239
	v_mul_f32_e32 v240, v240, v252
	v_fma_f32 v240, v240, v206, v222
	v_lshlrev_b32_e32 v244, 16, v144
	v_fmac_f32_e32 v240, v146, v244
	v_mul_f32_e32 v240, v114, v240
	v_mul_f32_e32 v241, v241, v252
	v_fma_f32 v241, v241, v207, v223
	v_and_b32_e32 v244, 0xffff0000, v144
	v_fmac_f32_e32 v241, v146, v244
	v_mul_f32_e32 v241, v115, v241
	v_mul_f32_e32 v242, v242, v252
	v_fma_f32 v242, v242, v208, v224
	v_lshlrev_b32_e32 v244, 16, v145
	v_fmac_f32_e32 v242, v146, v244
	v_mul_f32_e32 v242, v116, v242
	v_mul_f32_e32 v243, v243, v252
	v_fma_f32 v243, v243, v209, v225
	v_and_b32_e32 v244, 0xffff0000, v145
	v_fmac_f32_e32 v243, v146, v244
	v_mul_f32_e32 v243, v117, v243
	v_cvt_pk_bf16_f32 v240, v240, v241
	v_cvt_pk_bf16_f32 v241, v242, v243
	v_mov_b64_e32 v[248:249], v[148:149]
	s_add_i32 s0, s19, 32
	v_add_u32_e32 v253, s0, v0
	v_cmp_gt_i32_e32 vcc, s14, v253
	s_nop 1
	v_cndmask_b32_e32 v253, v168, v253, vcc
	v_mov_b64_e32 v[148:149], s[88:89]
	v_mad_i64_i32 v[148:149], s[0:1], v253, s15, v[148:149]
	v_mov_b32_e32 v244, v254
	v_mov_b32_e32 v245, 0
	v_lshl_add_u64 v[148:149], v[148:149], 0, v[244:245]
	global_load_dwordx2 v[130:131], v[148:149], off offset:0
	global_load_dwordx2 v[132:133], v[148:149], off offset:32
	global_load_dwordx2 v[134:135], v[148:149], off offset:64
	global_load_dwordx2 v[136:137], v[148:149], off offset:96
	v_ashrrev_i32_e32 v251, 31, v253
	v_mov_b32_e32 v250, v253
	v_lshlrev_b64 v[246:247], 11, v[250:251]
	v_lshl_add_u64 v[246:247], s[54:55], 0, v[246:247]
	v_lshl_add_u64 v[246:247], v[246:247], 0, v[244:245]
	global_load_dwordx2 v[138:139], v[246:247], off offset:0
	global_load_dwordx2 v[140:141], v[246:247], off offset:32
	global_load_dwordx2 v[142:143], v[246:247], off offset:64
	global_load_dwordx2 v[144:145], v[246:247], off offset:96
	v_lshlrev_b64 v[246:247], 6, v[250:251]
	v_lshl_add_u64 v[246:247], s[58:59], 0, v[246:247]
	v_lshl_add_u64 v[246:247], v[246:247], 0, s[20:21]
	global_load_dword v146, v[246:247], off
	s_add_i32 s0, s19, 0
	v_add_u32_e32 v253, s0, v0
	v_cmp_gt_i32_e32 vcc, s14, v253
	s_and_saveexec_b64 s[0:1], vcc
	global_store_dwordx2 v[248:249], v[228:229], off offset:0
	global_store_dwordx2 v[248:249], v[232:233], off offset:32
	global_store_dwordx2 v[248:249], v[236:237], off offset:64
	global_store_dwordx2 v[248:249], v[240:241], off offset:96
	s_or_b64 exec, exec, s[0:1]
	s_waitcnt vmcnt(9)
	v_lshlrev_b32_e32 v228, 16, v150
	v_and_b32_e32 v229, 0xffff0000, v150
	v_lshlrev_b32_e32 v230, 16, v151
	v_and_b32_e32 v231, 0xffff0000, v151
	v_lshlrev_b32_e32 v232, 16, v152
	v_and_b32_e32 v233, 0xffff0000, v152
	v_lshlrev_b32_e32 v234, 16, v153
	v_and_b32_e32 v235, 0xffff0000, v153
	v_lshlrev_b32_e32 v236, 16, v154
	v_and_b32_e32 v237, 0xffff0000, v154
	v_lshlrev_b32_e32 v238, 16, v155
	v_and_b32_e32 v239, 0xffff0000, v155
	v_lshlrev_b32_e32 v240, 16, v156
	v_and_b32_e32 v241, 0xffff0000, v156
	v_lshlrev_b32_e32 v242, 16, v157
	v_and_b32_e32 v243, 0xffff0000, v157
	v_add_f32_e32 v250, v228, v229
	v_add_f32_e32 v251, v230, v231
	v_add_f32_e32 v250, v250, v232
	v_add_f32_e32 v251, v251, v233
	v_add_f32_e32 v250, v250, v234
	v_add_f32_e32 v251, v251, v235
	v_add_f32_e32 v250, v250, v236
	v_add_f32_e32 v251, v251, v237
	v_add_f32_e32 v250, v250, v238
	v_add_f32_e32 v251, v251, v239
	v_add_f32_e32 v250, v250, v240
	v_add_f32_e32 v251, v251, v241
	v_add_f32_e32 v250, v250, v242
	v_add_f32_e32 v251, v251, v243
	v_add_f32_e32 v250, v250, v251
	ds_bpermute_b32 v251, v255, v250
	s_waitcnt lgkmcnt(0)
	v_add_f32_e32 v250, v250, v251
	ds_bpermute_b32 v251, v193, v250
	s_waitcnt lgkmcnt(0)
	v_add_f32_e32 v250, v250, v251
	v_fmac_f32_e32 v228, 0xbc800000, v250
	v_fmac_f32_e32 v229, 0xbc800000, v250
	v_fmac_f32_e32 v230, 0xbc800000, v250
	v_fmac_f32_e32 v231, 0xbc800000, v250
	v_fmac_f32_e32 v232, 0xbc800000, v250
	v_fmac_f32_e32 v233, 0xbc800000, v250
	v_fmac_f32_e32 v234, 0xbc800000, v250
	v_fmac_f32_e32 v235, 0xbc800000, v250
	v_fmac_f32_e32 v236, 0xbc800000, v250
	v_fmac_f32_e32 v237, 0xbc800000, v250
	v_fmac_f32_e32 v238, 0xbc800000, v250
	v_fmac_f32_e32 v239, 0xbc800000, v250
	v_fmac_f32_e32 v240, 0xbc800000, v250
	v_fmac_f32_e32 v241, 0xbc800000, v250
	v_fmac_f32_e32 v242, 0xbc800000, v250
	v_fmac_f32_e32 v243, 0xbc800000, v250
	v_mul_f32_e32 v250, v228, v228
	v_mul_f32_e32 v251, v229, v229
	v_fmac_f32_e32 v250, v230, v230
	v_fmac_f32_e32 v251, v231, v231
	v_fmac_f32_e32 v250, v232, v232
	v_fmac_f32_e32 v251, v233, v233
	v_fmac_f32_e32 v250, v234, v234
	v_fmac_f32_e32 v251, v235, v235
	v_fmac_f32_e32 v250, v236, v236
	v_fmac_f32_e32 v251, v237, v237
	v_fmac_f32_e32 v250, v238, v238
	v_fmac_f32_e32 v251, v239, v239
	v_fmac_f32_e32 v250, v240, v240
	v_fmac_f32_e32 v251, v241, v241
	v_fmac_f32_e32 v250, v242, v242
	v_fmac_f32_e32 v251, v243, v243
	v_add_f32_e32 v250, v250, v251
	ds_bpermute_b32 v251, v255, v250
	s_waitcnt lgkmcnt(0)
	v_add_f32_e32 v250, v250, v251
	ds_bpermute_b32 v251, v193, v250
	s_waitcnt lgkmcnt(0)
	v_add_f32_e32 v250, v250, v251
	v_fmamk_f32 v250, v250, 0x3c800000, v166
	v_mul_f32_e32 v251, 0x4b800000, v250
	v_cmp_gt_f32_e64 s[0:1], s16, v250
	s_nop 1
	v_cndmask_b32_e64 v250, v250, v251, s[0:1]
	v_rsq_f32_e32 v252, v250
	s_nop 0
	v_mul_f32_e32 v251, 0x45800000, v252
	v_cndmask_b32_e64 v252, v252, v251, s[0:1]
	v_mul_f32_e32 v228, v228, v252
	v_fma_f32 v228, v228, v194, v210
	v_lshlrev_b32_e32 v244, 16, v158
	v_fmac_f32_e32 v228, v147, v244
	v_mul_f32_e32 v228, v110, v228
	v_mul_f32_e32 v229, v229, v252
	v_fma_f32 v229, v229, v195, v211
	v_and_b32_e32 v244, 0xffff0000, v158
	v_fmac_f32_e32 v229, v147, v244
	v_mul_f32_e32 v229, v111, v229
	v_mul_f32_e32 v230, v230, v252
	v_fma_f32 v230, v230, v196, v212
	v_lshlrev_b32_e32 v244, 16, v159
	v_fmac_f32_e32 v230, v147, v244
	v_mul_f32_e32 v230, v112, v230
	v_mul_f32_e32 v231, v231, v252
	v_fma_f32 v231, v231, v197, v213
	v_and_b32_e32 v244, 0xffff0000, v159
	v_fmac_f32_e32 v231, v147, v244
	v_mul_f32_e32 v231, v113, v231
	v_cvt_pk_bf16_f32 v228, v228, v229
	v_cvt_pk_bf16_f32 v229, v230, v231
	v_mul_f32_e32 v232, v232, v252
	v_fma_f32 v232, v232, v198, v214
	v_lshlrev_b32_e32 v244, 16, v160
	v_fmac_f32_e32 v232, v147, v244
	v_mul_f32_e32 v232, v106, v232
	v_mul_f32_e32 v233, v233, v252
	v_fma_f32 v233, v233, v199, v215
	v_and_b32_e32 v244, 0xffff0000, v160
	v_fmac_f32_e32 v233, v147, v244
	v_mul_f32_e32 v233, v107, v233
	v_mul_f32_e32 v234, v234, v252
	v_fma_f32 v234, v234, v200, v216
	v_lshlrev_b32_e32 v244, 16, v161
	v_fmac_f32_e32 v234, v147, v244
	v_mul_f32_e32 v234, v108, v234
	v_mul_f32_e32 v235, v235, v252
	v_fma_f32 v235, v235, v201, v217
	v_and_b32_e32 v244, 0xffff0000, v161
	v_fmac_f32_e32 v235, v147, v244
	v_mul_f32_e32 v235, v109, v235
	v_cvt_pk_bf16_f32 v232, v232, v233
	v_cvt_pk_bf16_f32 v233, v234, v235
	v_mul_f32_e32 v236, v236, v252
	v_fma_f32 v236, v236, v202, v218
	v_lshlrev_b32_e32 v244, 16, v162
	v_fmac_f32_e32 v236, v147, v244
	v_mul_f32_e32 v236, v102, v236
	v_mul_f32_e32 v237, v237, v252
	v_fma_f32 v237, v237, v203, v219
	v_and_b32_e32 v244, 0xffff0000, v162
	v_fmac_f32_e32 v237, v147, v244
	v_mul_f32_e32 v237, v103, v237
	v_mul_f32_e32 v238, v238, v252
	v_fma_f32 v238, v238, v204, v220
	v_lshlrev_b32_e32 v244, 16, v163
	v_fmac_f32_e32 v238, v147, v244
	v_mul_f32_e32 v238, v104, v238
	v_mul_f32_e32 v239, v239, v252
	v_fma_f32 v239, v239, v205, v221
	v_and_b32_e32 v244, 0xffff0000, v163
	v_fmac_f32_e32 v239, v147, v244
	v_mul_f32_e32 v239, v105, v239
	v_cvt_pk_bf16_f32 v236, v236, v237
	v_cvt_pk_bf16_f32 v237, v238, v239
	v_mul_f32_e32 v240, v240, v252
	v_fma_f32 v240, v240, v206, v222
	v_lshlrev_b32_e32 v244, 16, v164
	v_fmac_f32_e32 v240, v147, v244
	v_mul_f32_e32 v240, v98, v240
	v_mul_f32_e32 v241, v241, v252
	v_fma_f32 v241, v241, v207, v223
	v_and_b32_e32 v244, 0xffff0000, v164
	v_fmac_f32_e32 v241, v147, v244
	v_mul_f32_e32 v241, v99, v241
	v_mul_f32_e32 v242, v242, v252
	v_fma_f32 v242, v242, v208, v224
	v_lshlrev_b32_e32 v244, 16, v165
	v_fmac_f32_e32 v242, v147, v244
	v_mul_f32_e32 v242, v100, v242
	v_mul_f32_e32 v243, v243, v252
	v_fma_f32 v243, v243, v209, v225
	v_and_b32_e32 v244, 0xffff0000, v165
	v_fmac_f32_e32 v243, v147, v244
	v_mul_f32_e32 v243, v101, v243
	v_cvt_pk_bf16_f32 v240, v240, v241
	v_cvt_pk_bf16_f32 v241, v242, v243
	v_mov_b64_e32 v[248:249], v[226:227]
	s_add_i32 s0, s19, 48
	v_add_u32_e32 v253, s0, v0
	v_cmp_gt_i32_e32 vcc, s14, v253
	s_nop 1
	v_cndmask_b32_e32 v253, v168, v253, vcc
	v_mov_b64_e32 v[226:227], s[88:89]
	v_mad_i64_i32 v[226:227], s[0:1], v253, s15, v[226:227]
	v_mov_b32_e32 v244, v254
	v_mov_b32_e32 v245, 0
	v_lshl_add_u64 v[226:227], v[226:227], 0, v[244:245]
	global_load_dwordx2 v[150:151], v[226:227], off offset:0
	global_load_dwordx2 v[152:153], v[226:227], off offset:32
	global_load_dwordx2 v[154:155], v[226:227], off offset:64
	global_load_dwordx2 v[156:157], v[226:227], off offset:96
	v_ashrrev_i32_e32 v251, 31, v253
	v_mov_b32_e32 v250, v253
	v_lshlrev_b64 v[246:247], 11, v[250:251]
	v_lshl_add_u64 v[246:247], s[54:55], 0, v[246:247]
	v_lshl_add_u64 v[246:247], v[246:247], 0, v[244:245]
	global_load_dwordx2 v[158:159], v[246:247], off offset:0
	global_load_dwordx2 v[160:161], v[246:247], off offset:32
	global_load_dwordx2 v[162:163], v[246:247], off offset:64
	global_load_dwordx2 v[164:165], v[246:247], off offset:96
	v_lshlrev_b64 v[246:247], 6, v[250:251]
	v_lshl_add_u64 v[246:247], s[58:59], 0, v[246:247]
	v_lshl_add_u64 v[246:247], v[246:247], 0, s[20:21]
	global_load_dword v147, v[246:247], off
	s_add_i32 s0, s19, 16
	v_add_u32_e32 v253, s0, v0
	v_cmp_gt_i32_e32 vcc, s14, v253
	s_and_saveexec_b64 s[0:1], vcc
	global_store_dwordx2 v[248:249], v[228:229], off offset:0
	global_store_dwordx2 v[248:249], v[232:233], off offset:32
	global_store_dwordx2 v[248:249], v[236:237], off offset:64
	global_store_dwordx2 v[248:249], v[240:241], off offset:96
	s_or_b64 exec, exec, s[0:1]
	s_waitcnt vmcnt(9)
	v_lshlrev_b32_e32 v228, 16, v130
	v_and_b32_e32 v229, 0xffff0000, v130
	v_lshlrev_b32_e32 v230, 16, v131
	v_and_b32_e32 v231, 0xffff0000, v131
	v_lshlrev_b32_e32 v232, 16, v132
	v_and_b32_e32 v233, 0xffff0000, v132
	v_lshlrev_b32_e32 v234, 16, v133
	v_and_b32_e32 v235, 0xffff0000, v133
	v_lshlrev_b32_e32 v236, 16, v134
	v_and_b32_e32 v237, 0xffff0000, v134
	v_lshlrev_b32_e32 v238, 16, v135
	v_and_b32_e32 v239, 0xffff0000, v135
	v_lshlrev_b32_e32 v240, 16, v136
	v_and_b32_e32 v241, 0xffff0000, v136
	v_lshlrev_b32_e32 v242, 16, v137
	v_and_b32_e32 v243, 0xffff0000, v137
	v_add_f32_e32 v250, v228, v229
	v_add_f32_e32 v251, v230, v231
	v_add_f32_e32 v250, v250, v232
	v_add_f32_e32 v251, v251, v233
	v_add_f32_e32 v250, v250, v234
	v_add_f32_e32 v251, v251, v235
	v_add_f32_e32 v250, v250, v236
	v_add_f32_e32 v251, v251, v237
	v_add_f32_e32 v250, v250, v238
	v_add_f32_e32 v251, v251, v239
	v_add_f32_e32 v250, v250, v240
	v_add_f32_e32 v251, v251, v241
	v_add_f32_e32 v250, v250, v242
	v_add_f32_e32 v251, v251, v243
	v_add_f32_e32 v250, v250, v251
	ds_bpermute_b32 v251, v255, v250
	s_waitcnt lgkmcnt(0)
	v_add_f32_e32 v250, v250, v251
	ds_bpermute_b32 v251, v193, v250
	s_waitcnt lgkmcnt(0)
	v_add_f32_e32 v250, v250, v251
	v_fmac_f32_e32 v228, 0xbc800000, v250
	v_fmac_f32_e32 v229, 0xbc800000, v250
	v_fmac_f32_e32 v230, 0xbc800000, v250
	v_fmac_f32_e32 v231, 0xbc800000, v250
	v_fmac_f32_e32 v232, 0xbc800000, v250
	v_fmac_f32_e32 v233, 0xbc800000, v250
	v_fmac_f32_e32 v234, 0xbc800000, v250
	v_fmac_f32_e32 v235, 0xbc800000, v250
	v_fmac_f32_e32 v236, 0xbc800000, v250
	v_fmac_f32_e32 v237, 0xbc800000, v250
	v_fmac_f32_e32 v238, 0xbc800000, v250
	v_fmac_f32_e32 v239, 0xbc800000, v250
	v_fmac_f32_e32 v240, 0xbc800000, v250
	v_fmac_f32_e32 v241, 0xbc800000, v250
	v_fmac_f32_e32 v242, 0xbc800000, v250
	v_fmac_f32_e32 v243, 0xbc800000, v250
	v_mul_f32_e32 v250, v228, v228
	v_mul_f32_e32 v251, v229, v229
	v_fmac_f32_e32 v250, v230, v230
	v_fmac_f32_e32 v251, v231, v231
	v_fmac_f32_e32 v250, v232, v232
	v_fmac_f32_e32 v251, v233, v233
	v_fmac_f32_e32 v250, v234, v234
	v_fmac_f32_e32 v251, v235, v235
	v_fmac_f32_e32 v250, v236, v236
	v_fmac_f32_e32 v251, v237, v237
	v_fmac_f32_e32 v250, v238, v238
	v_fmac_f32_e32 v251, v239, v239
	v_fmac_f32_e32 v250, v240, v240
	v_fmac_f32_e32 v251, v241, v241
	v_fmac_f32_e32 v250, v242, v242
	v_fmac_f32_e32 v251, v243, v243
	v_add_f32_e32 v250, v250, v251
	ds_bpermute_b32 v251, v255, v250
	s_waitcnt lgkmcnt(0)
	v_add_f32_e32 v250, v250, v251
	ds_bpermute_b32 v251, v193, v250
	s_waitcnt lgkmcnt(0)
	v_add_f32_e32 v250, v250, v251
	v_fmamk_f32 v250, v250, 0x3c800000, v166
	v_mul_f32_e32 v251, 0x4b800000, v250
	v_cmp_gt_f32_e64 s[0:1], s16, v250
	s_nop 1
	v_cndmask_b32_e64 v250, v250, v251, s[0:1]
	v_rsq_f32_e32 v252, v250
	s_nop 0
	v_mul_f32_e32 v251, 0x45800000, v252
	v_cndmask_b32_e64 v252, v252, v251, s[0:1]
	v_mul_f32_e32 v228, v228, v252
	v_fma_f32 v228, v228, v194, v210
	v_lshlrev_b32_e32 v244, 16, v138
	v_fmac_f32_e32 v228, v146, v244
	v_mul_f32_e32 v228, v94, v228
	v_mul_f32_e32 v229, v229, v252
	v_fma_f32 v229, v229, v195, v211
	v_and_b32_e32 v244, 0xffff0000, v138
	v_fmac_f32_e32 v229, v146, v244
	v_mul_f32_e32 v229, v95, v229
	v_mul_f32_e32 v230, v230, v252
	v_fma_f32 v230, v230, v196, v212
	v_lshlrev_b32_e32 v244, 16, v139
	v_fmac_f32_e32 v230, v146, v244
	v_mul_f32_e32 v230, v96, v230
	v_mul_f32_e32 v231, v231, v252
	v_fma_f32 v231, v231, v197, v213
	v_and_b32_e32 v244, 0xffff0000, v139
	v_fmac_f32_e32 v231, v146, v244
	v_mul_f32_e32 v231, v97, v231
	v_cvt_pk_bf16_f32 v228, v228, v229
	v_cvt_pk_bf16_f32 v229, v230, v231
	v_mul_f32_e32 v232, v232, v252
	v_fma_f32 v232, v232, v198, v214
	v_lshlrev_b32_e32 v244, 16, v140
	v_fmac_f32_e32 v232, v146, v244
	v_mul_f32_e32 v232, v90, v232
	v_mul_f32_e32 v233, v233, v252
	v_fma_f32 v233, v233, v199, v215
	v_and_b32_e32 v244, 0xffff0000, v140
	v_fmac_f32_e32 v233, v146, v244
	v_mul_f32_e32 v233, v91, v233
	v_mul_f32_e32 v234, v234, v252
	v_fma_f32 v234, v234, v200, v216
	v_lshlrev_b32_e32 v244, 16, v141
	v_fmac_f32_e32 v234, v146, v244
	v_mul_f32_e32 v234, v92, v234
	v_mul_f32_e32 v235, v235, v252
	v_fma_f32 v235, v235, v201, v217
	v_and_b32_e32 v244, 0xffff0000, v141
	v_fmac_f32_e32 v235, v146, v244
	v_mul_f32_e32 v235, v93, v235
	v_cvt_pk_bf16_f32 v232, v232, v233
	v_cvt_pk_bf16_f32 v233, v234, v235
	v_mul_f32_e32 v236, v236, v252
	v_fma_f32 v236, v236, v202, v218
	v_lshlrev_b32_e32 v244, 16, v142
	v_fmac_f32_e32 v236, v146, v244
	v_mul_f32_e32 v236, v86, v236
	v_mul_f32_e32 v237, v237, v252
	v_fma_f32 v237, v237, v203, v219
	v_and_b32_e32 v244, 0xffff0000, v142
	v_fmac_f32_e32 v237, v146, v244
	v_mul_f32_e32 v237, v87, v237
	v_mul_f32_e32 v238, v238, v252
	v_fma_f32 v238, v238, v204, v220
	v_lshlrev_b32_e32 v244, 16, v143
	v_fmac_f32_e32 v238, v146, v244
	v_mul_f32_e32 v238, v88, v238
	v_mul_f32_e32 v239, v239, v252
	v_fma_f32 v239, v239, v205, v221
	v_and_b32_e32 v244, 0xffff0000, v143
	v_fmac_f32_e32 v239, v146, v244
	v_mul_f32_e32 v239, v89, v239
	v_cvt_pk_bf16_f32 v236, v236, v237
	v_cvt_pk_bf16_f32 v237, v238, v239
	v_mul_f32_e32 v240, v240, v252
	v_fma_f32 v240, v240, v206, v222
	v_lshlrev_b32_e32 v244, 16, v144
	v_fmac_f32_e32 v240, v146, v244
	v_mul_f32_e32 v240, v82, v240
	v_mul_f32_e32 v241, v241, v252
	v_fma_f32 v241, v241, v207, v223
	v_and_b32_e32 v244, 0xffff0000, v144
	v_fmac_f32_e32 v241, v146, v244
	v_mul_f32_e32 v241, v83, v241
	v_mul_f32_e32 v242, v242, v252
	v_fma_f32 v242, v242, v208, v224
	v_lshlrev_b32_e32 v244, 16, v145
	v_fmac_f32_e32 v242, v146, v244
	v_mul_f32_e32 v242, v84, v242
	v_mul_f32_e32 v243, v243, v252
	v_fma_f32 v243, v243, v209, v225
	v_and_b32_e32 v244, 0xffff0000, v145
	v_fmac_f32_e32 v243, v146, v244
	v_mul_f32_e32 v243, v85, v243
	v_cvt_pk_bf16_f32 v240, v240, v241
	v_cvt_pk_bf16_f32 v241, v242, v243
	v_mov_b64_e32 v[248:249], v[148:149]
	s_add_i32 s0, s19, 64
	v_add_u32_e32 v253, s0, v0
	v_cmp_gt_i32_e32 vcc, s14, v253
	s_nop 1
	v_cndmask_b32_e32 v253, v168, v253, vcc
	v_mov_b64_e32 v[148:149], s[88:89]
	v_mad_i64_i32 v[148:149], s[0:1], v253, s15, v[148:149]
	v_mov_b32_e32 v244, v254
	v_mov_b32_e32 v245, 0
	v_lshl_add_u64 v[148:149], v[148:149], 0, v[244:245]
	global_load_dwordx2 v[130:131], v[148:149], off offset:0
	global_load_dwordx2 v[132:133], v[148:149], off offset:32
	global_load_dwordx2 v[134:135], v[148:149], off offset:64
	global_load_dwordx2 v[136:137], v[148:149], off offset:96
	v_ashrrev_i32_e32 v251, 31, v253
	v_mov_b32_e32 v250, v253
	v_lshlrev_b64 v[246:247], 11, v[250:251]
	v_lshl_add_u64 v[246:247], s[54:55], 0, v[246:247]
	v_lshl_add_u64 v[246:247], v[246:247], 0, v[244:245]
	global_load_dwordx2 v[138:139], v[246:247], off offset:0
	global_load_dwordx2 v[140:141], v[246:247], off offset:32
	global_load_dwordx2 v[142:143], v[246:247], off offset:64
	global_load_dwordx2 v[144:145], v[246:247], off offset:96
	v_lshlrev_b64 v[246:247], 6, v[250:251]
	v_lshl_add_u64 v[246:247], s[58:59], 0, v[246:247]
	v_lshl_add_u64 v[246:247], v[246:247], 0, s[20:21]
	global_load_dword v146, v[246:247], off
	s_add_i32 s0, s19, 32
	v_add_u32_e32 v253, s0, v0
	v_cmp_gt_i32_e32 vcc, s14, v253
	s_and_saveexec_b64 s[0:1], vcc
	global_store_dwordx2 v[248:249], v[228:229], off offset:0
	global_store_dwordx2 v[248:249], v[232:233], off offset:32
	global_store_dwordx2 v[248:249], v[236:237], off offset:64
	global_store_dwordx2 v[248:249], v[240:241], off offset:96
	s_or_b64 exec, exec, s[0:1]
	s_waitcnt vmcnt(9)
	v_lshlrev_b32_e32 v228, 16, v150
	v_and_b32_e32 v229, 0xffff0000, v150
	v_lshlrev_b32_e32 v230, 16, v151
	v_and_b32_e32 v231, 0xffff0000, v151
	v_lshlrev_b32_e32 v232, 16, v152
	v_and_b32_e32 v233, 0xffff0000, v152
	v_lshlrev_b32_e32 v234, 16, v153
	v_and_b32_e32 v235, 0xffff0000, v153
	v_lshlrev_b32_e32 v236, 16, v154
	v_and_b32_e32 v237, 0xffff0000, v154
	v_lshlrev_b32_e32 v238, 16, v155
	v_and_b32_e32 v239, 0xffff0000, v155
	v_lshlrev_b32_e32 v240, 16, v156
	v_and_b32_e32 v241, 0xffff0000, v156
	v_lshlrev_b32_e32 v242, 16, v157
	v_and_b32_e32 v243, 0xffff0000, v157
	v_add_f32_e32 v250, v228, v229
	v_add_f32_e32 v251, v230, v231
	v_add_f32_e32 v250, v250, v232
	v_add_f32_e32 v251, v251, v233
	v_add_f32_e32 v250, v250, v234
	v_add_f32_e32 v251, v251, v235
	v_add_f32_e32 v250, v250, v236
	v_add_f32_e32 v251, v251, v237
	v_add_f32_e32 v250, v250, v238
	v_add_f32_e32 v251, v251, v239
	v_add_f32_e32 v250, v250, v240
	v_add_f32_e32 v251, v251, v241
	v_add_f32_e32 v250, v250, v242
	v_add_f32_e32 v251, v251, v243
	v_add_f32_e32 v250, v250, v251
	ds_bpermute_b32 v251, v255, v250
	s_waitcnt lgkmcnt(0)
	v_add_f32_e32 v250, v250, v251
	ds_bpermute_b32 v251, v193, v250
	s_waitcnt lgkmcnt(0)
	v_add_f32_e32 v250, v250, v251
	v_fmac_f32_e32 v228, 0xbc800000, v250
	v_fmac_f32_e32 v229, 0xbc800000, v250
	v_fmac_f32_e32 v230, 0xbc800000, v250
	v_fmac_f32_e32 v231, 0xbc800000, v250
	v_fmac_f32_e32 v232, 0xbc800000, v250
	v_fmac_f32_e32 v233, 0xbc800000, v250
	v_fmac_f32_e32 v234, 0xbc800000, v250
	v_fmac_f32_e32 v235, 0xbc800000, v250
	v_fmac_f32_e32 v236, 0xbc800000, v250
	v_fmac_f32_e32 v237, 0xbc800000, v250
	v_fmac_f32_e32 v238, 0xbc800000, v250
	v_fmac_f32_e32 v239, 0xbc800000, v250
	v_fmac_f32_e32 v240, 0xbc800000, v250
	v_fmac_f32_e32 v241, 0xbc800000, v250
	v_fmac_f32_e32 v242, 0xbc800000, v250
	v_fmac_f32_e32 v243, 0xbc800000, v250
	v_mul_f32_e32 v250, v228, v228
	v_mul_f32_e32 v251, v229, v229
	v_fmac_f32_e32 v250, v230, v230
	v_fmac_f32_e32 v251, v231, v231
	v_fmac_f32_e32 v250, v232, v232
	v_fmac_f32_e32 v251, v233, v233
	v_fmac_f32_e32 v250, v234, v234
	v_fmac_f32_e32 v251, v235, v235
	v_fmac_f32_e32 v250, v236, v236
	v_fmac_f32_e32 v251, v237, v237
	v_fmac_f32_e32 v250, v238, v238
	v_fmac_f32_e32 v251, v239, v239
	v_fmac_f32_e32 v250, v240, v240
	v_fmac_f32_e32 v251, v241, v241
	v_fmac_f32_e32 v250, v242, v242
	v_fmac_f32_e32 v251, v243, v243
	v_add_f32_e32 v250, v250, v251
	ds_bpermute_b32 v251, v255, v250
	s_waitcnt lgkmcnt(0)
	v_add_f32_e32 v250, v250, v251
	ds_bpermute_b32 v251, v193, v250
	s_waitcnt lgkmcnt(0)
	v_add_f32_e32 v250, v250, v251
	v_fmamk_f32 v250, v250, 0x3c800000, v166
	v_mul_f32_e32 v251, 0x4b800000, v250
	v_cmp_gt_f32_e64 s[0:1], s16, v250
	s_nop 1
	v_cndmask_b32_e64 v250, v250, v251, s[0:1]
	v_rsq_f32_e32 v252, v250
	s_nop 0
	v_mul_f32_e32 v251, 0x45800000, v252
	v_cndmask_b32_e64 v252, v252, v251, s[0:1]
	v_mul_f32_e32 v228, v228, v252
	v_fma_f32 v228, v228, v194, v210
	v_lshlrev_b32_e32 v244, 16, v158
	v_fmac_f32_e32 v228, v147, v244
	v_mul_f32_e32 v228, v78, v228
	v_mul_f32_e32 v229, v229, v252
	v_fma_f32 v229, v229, v195, v211
	v_and_b32_e32 v244, 0xffff0000, v158
	v_fmac_f32_e32 v229, v147, v244
	v_mul_f32_e32 v229, v79, v229
	v_mul_f32_e32 v230, v230, v252
	v_fma_f32 v230, v230, v196, v212
	v_lshlrev_b32_e32 v244, 16, v159
	v_fmac_f32_e32 v230, v147, v244
	v_mul_f32_e32 v230, v80, v230
	v_mul_f32_e32 v231, v231, v252
	v_fma_f32 v231, v231, v197, v213
	v_and_b32_e32 v244, 0xffff0000, v159
	v_fmac_f32_e32 v231, v147, v244
	v_mul_f32_e32 v231, v81, v231
	v_cvt_pk_bf16_f32 v228, v228, v229
	v_cvt_pk_bf16_f32 v229, v230, v231
	v_mul_f32_e32 v232, v232, v252
	v_fma_f32 v232, v232, v198, v214
	v_lshlrev_b32_e32 v244, 16, v160
	v_fmac_f32_e32 v232, v147, v244
	v_mul_f32_e32 v232, v74, v232
	v_mul_f32_e32 v233, v233, v252
	v_fma_f32 v233, v233, v199, v215
	v_and_b32_e32 v244, 0xffff0000, v160
	v_fmac_f32_e32 v233, v147, v244
	v_mul_f32_e32 v233, v75, v233
	v_mul_f32_e32 v234, v234, v252
	v_fma_f32 v234, v234, v200, v216
	v_lshlrev_b32_e32 v244, 16, v161
	v_fmac_f32_e32 v234, v147, v244
	v_mul_f32_e32 v234, v76, v234
	v_mul_f32_e32 v235, v235, v252
	v_fma_f32 v235, v235, v201, v217
	v_and_b32_e32 v244, 0xffff0000, v161
	v_fmac_f32_e32 v235, v147, v244
	v_mul_f32_e32 v235, v77, v235
	v_cvt_pk_bf16_f32 v232, v232, v233
	v_cvt_pk_bf16_f32 v233, v234, v235
	v_mul_f32_e32 v236, v236, v252
	v_fma_f32 v236, v236, v202, v218
	v_lshlrev_b32_e32 v244, 16, v162
	v_fmac_f32_e32 v236, v147, v244
	v_mul_f32_e32 v236, v70, v236
	v_mul_f32_e32 v237, v237, v252
	v_fma_f32 v237, v237, v203, v219
	v_and_b32_e32 v244, 0xffff0000, v162
	v_fmac_f32_e32 v237, v147, v244
	v_mul_f32_e32 v237, v71, v237
	v_mul_f32_e32 v238, v238, v252
	v_fma_f32 v238, v238, v204, v220
	v_lshlrev_b32_e32 v244, 16, v163
	v_fmac_f32_e32 v238, v147, v244
	v_mul_f32_e32 v238, v72, v238
	v_mul_f32_e32 v239, v239, v252
	v_fma_f32 v239, v239, v205, v221
	v_and_b32_e32 v244, 0xffff0000, v163
	v_fmac_f32_e32 v239, v147, v244
	v_mul_f32_e32 v239, v73, v239
	v_cvt_pk_bf16_f32 v236, v236, v237
	v_cvt_pk_bf16_f32 v237, v238, v239
	v_mul_f32_e32 v240, v240, v252
	v_fma_f32 v240, v240, v206, v222
	v_lshlrev_b32_e32 v244, 16, v164
	v_fmac_f32_e32 v240, v147, v244
	v_mul_f32_e32 v240, v66, v240
	v_mul_f32_e32 v241, v241, v252
	v_fma_f32 v241, v241, v207, v223
	v_and_b32_e32 v244, 0xffff0000, v164
	v_fmac_f32_e32 v241, v147, v244
	v_mul_f32_e32 v241, v67, v241
	v_mul_f32_e32 v242, v242, v252
	v_fma_f32 v242, v242, v208, v224
	v_lshlrev_b32_e32 v244, 16, v165
	v_fmac_f32_e32 v242, v147, v244
	v_mul_f32_e32 v242, v68, v242
	v_mul_f32_e32 v243, v243, v252
	v_fma_f32 v243, v243, v209, v225
	v_and_b32_e32 v244, 0xffff0000, v165
	v_fmac_f32_e32 v243, v147, v244
	v_mul_f32_e32 v243, v69, v243
	v_cvt_pk_bf16_f32 v240, v240, v241
	v_cvt_pk_bf16_f32 v241, v242, v243
	v_mov_b64_e32 v[248:249], v[226:227]
	s_add_i32 s0, s19, 80
	v_add_u32_e32 v253, s0, v0
	v_cmp_gt_i32_e32 vcc, s14, v253
	s_nop 1
	v_cndmask_b32_e32 v253, v168, v253, vcc
	v_mov_b64_e32 v[226:227], s[88:89]
	v_mad_i64_i32 v[226:227], s[0:1], v253, s15, v[226:227]
	v_mov_b32_e32 v244, v254
	v_mov_b32_e32 v245, 0
	v_lshl_add_u64 v[226:227], v[226:227], 0, v[244:245]
	global_load_dwordx2 v[150:151], v[226:227], off offset:0
	global_load_dwordx2 v[152:153], v[226:227], off offset:32
	global_load_dwordx2 v[154:155], v[226:227], off offset:64
	global_load_dwordx2 v[156:157], v[226:227], off offset:96
	v_ashrrev_i32_e32 v251, 31, v253
	v_mov_b32_e32 v250, v253
	v_lshlrev_b64 v[246:247], 11, v[250:251]
	v_lshl_add_u64 v[246:247], s[54:55], 0, v[246:247]
	v_lshl_add_u64 v[246:247], v[246:247], 0, v[244:245]
	global_load_dwordx2 v[158:159], v[246:247], off offset:0
	global_load_dwordx2 v[160:161], v[246:247], off offset:32
	global_load_dwordx2 v[162:163], v[246:247], off offset:64
	global_load_dwordx2 v[164:165], v[246:247], off offset:96
	v_lshlrev_b64 v[246:247], 6, v[250:251]
	v_lshl_add_u64 v[246:247], s[58:59], 0, v[246:247]
	v_lshl_add_u64 v[246:247], v[246:247], 0, s[20:21]
	global_load_dword v147, v[246:247], off
	s_add_i32 s0, s19, 48
	v_add_u32_e32 v253, s0, v0
	v_cmp_gt_i32_e32 vcc, s14, v253
	s_and_saveexec_b64 s[0:1], vcc
	global_store_dwordx2 v[248:249], v[228:229], off offset:0
	global_store_dwordx2 v[248:249], v[232:233], off offset:32
	global_store_dwordx2 v[248:249], v[236:237], off offset:64
	global_store_dwordx2 v[248:249], v[240:241], off offset:96
	s_or_b64 exec, exec, s[0:1]
	s_waitcnt vmcnt(9)
	v_lshlrev_b32_e32 v228, 16, v130
	v_and_b32_e32 v229, 0xffff0000, v130
	v_lshlrev_b32_e32 v230, 16, v131
	v_and_b32_e32 v231, 0xffff0000, v131
	v_lshlrev_b32_e32 v232, 16, v132
	v_and_b32_e32 v233, 0xffff0000, v132
	v_lshlrev_b32_e32 v234, 16, v133
	v_and_b32_e32 v235, 0xffff0000, v133
	v_lshlrev_b32_e32 v236, 16, v134
	v_and_b32_e32 v237, 0xffff0000, v134
	v_lshlrev_b32_e32 v238, 16, v135
	v_and_b32_e32 v239, 0xffff0000, v135
	v_lshlrev_b32_e32 v240, 16, v136
	v_and_b32_e32 v241, 0xffff0000, v136
	v_lshlrev_b32_e32 v242, 16, v137
	v_and_b32_e32 v243, 0xffff0000, v137
	v_add_f32_e32 v250, v228, v229
	v_add_f32_e32 v251, v230, v231
	v_add_f32_e32 v250, v250, v232
	v_add_f32_e32 v251, v251, v233
	v_add_f32_e32 v250, v250, v234
	v_add_f32_e32 v251, v251, v235
	v_add_f32_e32 v250, v250, v236
	v_add_f32_e32 v251, v251, v237
	v_add_f32_e32 v250, v250, v238
	v_add_f32_e32 v251, v251, v239
	v_add_f32_e32 v250, v250, v240
	v_add_f32_e32 v251, v251, v241
	v_add_f32_e32 v250, v250, v242
	v_add_f32_e32 v251, v251, v243
	v_add_f32_e32 v250, v250, v251
	ds_bpermute_b32 v251, v255, v250
	s_waitcnt lgkmcnt(0)
	v_add_f32_e32 v250, v250, v251
	ds_bpermute_b32 v251, v193, v250
	s_waitcnt lgkmcnt(0)
	v_add_f32_e32 v250, v250, v251
	v_fmac_f32_e32 v228, 0xbc800000, v250
	v_fmac_f32_e32 v229, 0xbc800000, v250
	v_fmac_f32_e32 v230, 0xbc800000, v250
	v_fmac_f32_e32 v231, 0xbc800000, v250
	v_fmac_f32_e32 v232, 0xbc800000, v250
	v_fmac_f32_e32 v233, 0xbc800000, v250
	v_fmac_f32_e32 v234, 0xbc800000, v250
	v_fmac_f32_e32 v235, 0xbc800000, v250
	v_fmac_f32_e32 v236, 0xbc800000, v250
	v_fmac_f32_e32 v237, 0xbc800000, v250
	v_fmac_f32_e32 v238, 0xbc800000, v250
	v_fmac_f32_e32 v239, 0xbc800000, v250
	v_fmac_f32_e32 v240, 0xbc800000, v250
	v_fmac_f32_e32 v241, 0xbc800000, v250
	v_fmac_f32_e32 v242, 0xbc800000, v250
	v_fmac_f32_e32 v243, 0xbc800000, v250
	v_mul_f32_e32 v250, v228, v228
	v_mul_f32_e32 v251, v229, v229
	v_fmac_f32_e32 v250, v230, v230
	v_fmac_f32_e32 v251, v231, v231
	v_fmac_f32_e32 v250, v232, v232
	v_fmac_f32_e32 v251, v233, v233
	v_fmac_f32_e32 v250, v234, v234
	v_fmac_f32_e32 v251, v235, v235
	v_fmac_f32_e32 v250, v236, v236
	v_fmac_f32_e32 v251, v237, v237
	v_fmac_f32_e32 v250, v238, v238
	v_fmac_f32_e32 v251, v239, v239
	v_fmac_f32_e32 v250, v240, v240
	v_fmac_f32_e32 v251, v241, v241
	v_fmac_f32_e32 v250, v242, v242
	v_fmac_f32_e32 v251, v243, v243
	v_add_f32_e32 v250, v250, v251
	ds_bpermute_b32 v251, v255, v250
	s_waitcnt lgkmcnt(0)
	v_add_f32_e32 v250, v250, v251
	ds_bpermute_b32 v251, v193, v250
	s_waitcnt lgkmcnt(0)
	v_add_f32_e32 v250, v250, v251
	v_fmamk_f32 v250, v250, 0x3c800000, v166
	v_mul_f32_e32 v251, 0x4b800000, v250
	v_cmp_gt_f32_e64 s[0:1], s16, v250
	s_nop 1
	v_cndmask_b32_e64 v250, v250, v251, s[0:1]
	v_rsq_f32_e32 v252, v250
	s_nop 0
	v_mul_f32_e32 v251, 0x45800000, v252
	v_cndmask_b32_e64 v252, v252, v251, s[0:1]
	v_mul_f32_e32 v228, v228, v252
	v_fma_f32 v228, v228, v194, v210
	v_lshlrev_b32_e32 v244, 16, v138
	v_fmac_f32_e32 v228, v146, v244
	v_mul_f32_e32 v228, v62, v228
	v_mul_f32_e32 v229, v229, v252
	v_fma_f32 v229, v229, v195, v211
	v_and_b32_e32 v244, 0xffff0000, v138
	v_fmac_f32_e32 v229, v146, v244
	v_mul_f32_e32 v229, v63, v229
	v_mul_f32_e32 v230, v230, v252
	v_fma_f32 v230, v230, v196, v212
	v_lshlrev_b32_e32 v244, 16, v139
	v_fmac_f32_e32 v230, v146, v244
	v_mul_f32_e32 v230, v64, v230
	v_mul_f32_e32 v231, v231, v252
	v_fma_f32 v231, v231, v197, v213
	v_and_b32_e32 v244, 0xffff0000, v139
	v_fmac_f32_e32 v231, v146, v244
	v_mul_f32_e32 v231, v65, v231
	v_cvt_pk_bf16_f32 v228, v228, v229
	v_cvt_pk_bf16_f32 v229, v230, v231
	v_mul_f32_e32 v232, v232, v252
	v_fma_f32 v232, v232, v198, v214
	v_lshlrev_b32_e32 v244, 16, v140
	v_fmac_f32_e32 v232, v146, v244
	v_mul_f32_e32 v232, v58, v232
	v_mul_f32_e32 v233, v233, v252
	v_fma_f32 v233, v233, v199, v215
	v_and_b32_e32 v244, 0xffff0000, v140
	v_fmac_f32_e32 v233, v146, v244
	v_mul_f32_e32 v233, v59, v233
	v_mul_f32_e32 v234, v234, v252
	v_fma_f32 v234, v234, v200, v216
	v_lshlrev_b32_e32 v244, 16, v141
	v_fmac_f32_e32 v234, v146, v244
	v_mul_f32_e32 v234, v60, v234
	v_mul_f32_e32 v235, v235, v252
	v_fma_f32 v235, v235, v201, v217
	v_and_b32_e32 v244, 0xffff0000, v141
	v_fmac_f32_e32 v235, v146, v244
	v_mul_f32_e32 v235, v61, v235
	v_cvt_pk_bf16_f32 v232, v232, v233
	v_cvt_pk_bf16_f32 v233, v234, v235
	v_mul_f32_e32 v236, v236, v252
	v_fma_f32 v236, v236, v202, v218
	v_lshlrev_b32_e32 v244, 16, v142
	v_fmac_f32_e32 v236, v146, v244
	v_mul_f32_e32 v236, v54, v236
	v_mul_f32_e32 v237, v237, v252
	v_fma_f32 v237, v237, v203, v219
	v_and_b32_e32 v244, 0xffff0000, v142
	v_fmac_f32_e32 v237, v146, v244
	v_mul_f32_e32 v237, v55, v237
	v_mul_f32_e32 v238, v238, v252
	v_fma_f32 v238, v238, v204, v220
	v_lshlrev_b32_e32 v244, 16, v143
	v_fmac_f32_e32 v238, v146, v244
	v_mul_f32_e32 v238, v56, v238
	v_mul_f32_e32 v239, v239, v252
	v_fma_f32 v239, v239, v205, v221
	v_and_b32_e32 v244, 0xffff0000, v143
	v_fmac_f32_e32 v239, v146, v244
	v_mul_f32_e32 v239, v57, v239
	v_cvt_pk_bf16_f32 v236, v236, v237
	v_cvt_pk_bf16_f32 v237, v238, v239
	v_mul_f32_e32 v240, v240, v252
	v_fma_f32 v240, v240, v206, v222
	v_lshlrev_b32_e32 v244, 16, v144
	v_fmac_f32_e32 v240, v146, v244
	v_mul_f32_e32 v240, v50, v240
	v_mul_f32_e32 v241, v241, v252
	v_fma_f32 v241, v241, v207, v223
	v_and_b32_e32 v244, 0xffff0000, v144
	v_fmac_f32_e32 v241, v146, v244
	v_mul_f32_e32 v241, v51, v241
	v_mul_f32_e32 v242, v242, v252
	v_fma_f32 v242, v242, v208, v224
	v_lshlrev_b32_e32 v244, 16, v145
	v_fmac_f32_e32 v242, v146, v244
	v_mul_f32_e32 v242, v52, v242
	v_mul_f32_e32 v243, v243, v252
	v_fma_f32 v243, v243, v209, v225
	v_and_b32_e32 v244, 0xffff0000, v145
	v_fmac_f32_e32 v243, v146, v244
	v_mul_f32_e32 v243, v53, v243
	v_cvt_pk_bf16_f32 v240, v240, v241
	v_cvt_pk_bf16_f32 v241, v242, v243
	v_mov_b64_e32 v[248:249], v[148:149]
	s_add_i32 s0, s19, 96
	v_add_u32_e32 v253, s0, v0
	v_cmp_gt_i32_e32 vcc, s14, v253
	s_nop 1
	v_cndmask_b32_e32 v253, v168, v253, vcc
	v_mov_b64_e32 v[148:149], s[88:89]
	v_mad_i64_i32 v[148:149], s[0:1], v253, s15, v[148:149]
	v_mov_b32_e32 v244, v254
	v_mov_b32_e32 v245, 0
	v_lshl_add_u64 v[148:149], v[148:149], 0, v[244:245]
	global_load_dwordx2 v[130:131], v[148:149], off offset:0
	global_load_dwordx2 v[132:133], v[148:149], off offset:32
	global_load_dwordx2 v[134:135], v[148:149], off offset:64
	global_load_dwordx2 v[136:137], v[148:149], off offset:96
	v_ashrrev_i32_e32 v251, 31, v253
	v_mov_b32_e32 v250, v253
	v_lshlrev_b64 v[246:247], 11, v[250:251]
	v_lshl_add_u64 v[246:247], s[54:55], 0, v[246:247]
	v_lshl_add_u64 v[246:247], v[246:247], 0, v[244:245]
	global_load_dwordx2 v[138:139], v[246:247], off offset:0
	global_load_dwordx2 v[140:141], v[246:247], off offset:32
	global_load_dwordx2 v[142:143], v[246:247], off offset:64
	global_load_dwordx2 v[144:145], v[246:247], off offset:96
	v_lshlrev_b64 v[246:247], 6, v[250:251]
	v_lshl_add_u64 v[246:247], s[58:59], 0, v[246:247]
	v_lshl_add_u64 v[246:247], v[246:247], 0, s[20:21]
	global_load_dword v146, v[246:247], off
	s_add_i32 s0, s19, 64
	v_add_u32_e32 v253, s0, v0
	v_cmp_gt_i32_e32 vcc, s14, v253
	s_and_saveexec_b64 s[0:1], vcc
	global_store_dwordx2 v[248:249], v[228:229], off offset:0
	global_store_dwordx2 v[248:249], v[232:233], off offset:32
	global_store_dwordx2 v[248:249], v[236:237], off offset:64
	global_store_dwordx2 v[248:249], v[240:241], off offset:96
	s_or_b64 exec, exec, s[0:1]
	s_waitcnt vmcnt(9)
	v_lshlrev_b32_e32 v228, 16, v150
	v_and_b32_e32 v229, 0xffff0000, v150
	v_lshlrev_b32_e32 v230, 16, v151
	v_and_b32_e32 v231, 0xffff0000, v151
	v_lshlrev_b32_e32 v232, 16, v152
	v_and_b32_e32 v233, 0xffff0000, v152
	v_lshlrev_b32_e32 v234, 16, v153
	v_and_b32_e32 v235, 0xffff0000, v153
	v_lshlrev_b32_e32 v236, 16, v154
	v_and_b32_e32 v237, 0xffff0000, v154
	v_lshlrev_b32_e32 v238, 16, v155
	v_and_b32_e32 v239, 0xffff0000, v155
	v_lshlrev_b32_e32 v240, 16, v156
	v_and_b32_e32 v241, 0xffff0000, v156
	v_lshlrev_b32_e32 v242, 16, v157
	v_and_b32_e32 v243, 0xffff0000, v157
	v_add_f32_e32 v250, v228, v229
	v_add_f32_e32 v251, v230, v231
	v_add_f32_e32 v250, v250, v232
	v_add_f32_e32 v251, v251, v233
	v_add_f32_e32 v250, v250, v234
	v_add_f32_e32 v251, v251, v235
	v_add_f32_e32 v250, v250, v236
	v_add_f32_e32 v251, v251, v237
	v_add_f32_e32 v250, v250, v238
	v_add_f32_e32 v251, v251, v239
	v_add_f32_e32 v250, v250, v240
	v_add_f32_e32 v251, v251, v241
	v_add_f32_e32 v250, v250, v242
	v_add_f32_e32 v251, v251, v243
	v_add_f32_e32 v250, v250, v251
	ds_bpermute_b32 v251, v255, v250
	s_waitcnt lgkmcnt(0)
	v_add_f32_e32 v250, v250, v251
	ds_bpermute_b32 v251, v193, v250
	s_waitcnt lgkmcnt(0)
	v_add_f32_e32 v250, v250, v251
	v_fmac_f32_e32 v228, 0xbc800000, v250
	v_fmac_f32_e32 v229, 0xbc800000, v250
	v_fmac_f32_e32 v230, 0xbc800000, v250
	v_fmac_f32_e32 v231, 0xbc800000, v250
	v_fmac_f32_e32 v232, 0xbc800000, v250
	v_fmac_f32_e32 v233, 0xbc800000, v250
	v_fmac_f32_e32 v234, 0xbc800000, v250
	v_fmac_f32_e32 v235, 0xbc800000, v250
	v_fmac_f32_e32 v236, 0xbc800000, v250
	v_fmac_f32_e32 v237, 0xbc800000, v250
	v_fmac_f32_e32 v238, 0xbc800000, v250
	v_fmac_f32_e32 v239, 0xbc800000, v250
	v_fmac_f32_e32 v240, 0xbc800000, v250
	v_fmac_f32_e32 v241, 0xbc800000, v250
	v_fmac_f32_e32 v242, 0xbc800000, v250
	v_fmac_f32_e32 v243, 0xbc800000, v250
	v_mul_f32_e32 v250, v228, v228
	v_mul_f32_e32 v251, v229, v229
	v_fmac_f32_e32 v250, v230, v230
	v_fmac_f32_e32 v251, v231, v231
	v_fmac_f32_e32 v250, v232, v232
	v_fmac_f32_e32 v251, v233, v233
	v_fmac_f32_e32 v250, v234, v234
	v_fmac_f32_e32 v251, v235, v235
	v_fmac_f32_e32 v250, v236, v236
	v_fmac_f32_e32 v251, v237, v237
	v_fmac_f32_e32 v250, v238, v238
	v_fmac_f32_e32 v251, v239, v239
	v_fmac_f32_e32 v250, v240, v240
	v_fmac_f32_e32 v251, v241, v241
	v_fmac_f32_e32 v250, v242, v242
	v_fmac_f32_e32 v251, v243, v243
	v_add_f32_e32 v250, v250, v251
	ds_bpermute_b32 v251, v255, v250
	s_waitcnt lgkmcnt(0)
	v_add_f32_e32 v250, v250, v251
	ds_bpermute_b32 v251, v193, v250
	s_waitcnt lgkmcnt(0)
	v_add_f32_e32 v250, v250, v251
	v_fmamk_f32 v250, v250, 0x3c800000, v166
	v_mul_f32_e32 v251, 0x4b800000, v250
	v_cmp_gt_f32_e64 s[0:1], s16, v250
	s_nop 1
	v_cndmask_b32_e64 v250, v250, v251, s[0:1]
	v_rsq_f32_e32 v252, v250
	s_nop 0
	v_mul_f32_e32 v251, 0x45800000, v252
	v_cndmask_b32_e64 v252, v252, v251, s[0:1]
	v_mul_f32_e32 v228, v228, v252
	v_fma_f32 v228, v228, v194, v210
	v_lshlrev_b32_e32 v244, 16, v158
	v_fmac_f32_e32 v228, v147, v244
	v_mul_f32_e32 v228, v46, v228
	v_mul_f32_e32 v229, v229, v252
	v_fma_f32 v229, v229, v195, v211
	v_and_b32_e32 v244, 0xffff0000, v158
	v_fmac_f32_e32 v229, v147, v244
	v_mul_f32_e32 v229, v47, v229
	v_mul_f32_e32 v230, v230, v252
	v_fma_f32 v230, v230, v196, v212
	v_lshlrev_b32_e32 v244, 16, v159
	v_fmac_f32_e32 v230, v147, v244
	v_mul_f32_e32 v230, v48, v230
	v_mul_f32_e32 v231, v231, v252
	v_fma_f32 v231, v231, v197, v213
	v_and_b32_e32 v244, 0xffff0000, v159
	v_fmac_f32_e32 v231, v147, v244
	v_mul_f32_e32 v231, v49, v231
	v_cvt_pk_bf16_f32 v228, v228, v229
	v_cvt_pk_bf16_f32 v229, v230, v231
	v_mul_f32_e32 v232, v232, v252
	v_fma_f32 v232, v232, v198, v214
	v_lshlrev_b32_e32 v244, 16, v160
	v_fmac_f32_e32 v232, v147, v244
	v_mul_f32_e32 v232, v42, v232
	v_mul_f32_e32 v233, v233, v252
	v_fma_f32 v233, v233, v199, v215
	v_and_b32_e32 v244, 0xffff0000, v160
	v_fmac_f32_e32 v233, v147, v244
	v_mul_f32_e32 v233, v43, v233
	v_mul_f32_e32 v234, v234, v252
	v_fma_f32 v234, v234, v200, v216
	v_lshlrev_b32_e32 v244, 16, v161
	v_fmac_f32_e32 v234, v147, v244
	v_mul_f32_e32 v234, v44, v234
	v_mul_f32_e32 v235, v235, v252
	v_fma_f32 v235, v235, v201, v217
	v_and_b32_e32 v244, 0xffff0000, v161
	v_fmac_f32_e32 v235, v147, v244
	v_mul_f32_e32 v235, v45, v235
	v_cvt_pk_bf16_f32 v232, v232, v233
	v_cvt_pk_bf16_f32 v233, v234, v235
	v_mul_f32_e32 v236, v236, v252
	v_fma_f32 v236, v236, v202, v218
	v_lshlrev_b32_e32 v244, 16, v162
	v_fmac_f32_e32 v236, v147, v244
	v_mul_f32_e32 v236, v38, v236
	v_mul_f32_e32 v237, v237, v252
	v_fma_f32 v237, v237, v203, v219
	v_and_b32_e32 v244, 0xffff0000, v162
	v_fmac_f32_e32 v237, v147, v244
	v_mul_f32_e32 v237, v39, v237
	v_mul_f32_e32 v238, v238, v252
	v_fma_f32 v238, v238, v204, v220
	v_lshlrev_b32_e32 v244, 16, v163
	v_fmac_f32_e32 v238, v147, v244
	v_mul_f32_e32 v238, v40, v238
	v_mul_f32_e32 v239, v239, v252
	v_fma_f32 v239, v239, v205, v221
	v_and_b32_e32 v244, 0xffff0000, v163
	v_fmac_f32_e32 v239, v147, v244
	v_mul_f32_e32 v239, v41, v239
	v_cvt_pk_bf16_f32 v236, v236, v237
	v_cvt_pk_bf16_f32 v237, v238, v239
	v_mul_f32_e32 v240, v240, v252
	v_fma_f32 v240, v240, v206, v222
	v_lshlrev_b32_e32 v244, 16, v164
	v_fmac_f32_e32 v240, v147, v244
	v_mul_f32_e32 v240, v34, v240
	v_mul_f32_e32 v241, v241, v252
	v_fma_f32 v241, v241, v207, v223
	v_and_b32_e32 v244, 0xffff0000, v164
	v_fmac_f32_e32 v241, v147, v244
	v_mul_f32_e32 v241, v35, v241
	v_mul_f32_e32 v242, v242, v252
	v_fma_f32 v242, v242, v208, v224
	v_lshlrev_b32_e32 v244, 16, v165
	v_fmac_f32_e32 v242, v147, v244
	v_mul_f32_e32 v242, v36, v242
	v_mul_f32_e32 v243, v243, v252
	v_fma_f32 v243, v243, v209, v225
	v_and_b32_e32 v244, 0xffff0000, v165
	v_fmac_f32_e32 v243, v147, v244
	v_mul_f32_e32 v243, v37, v243
	v_cvt_pk_bf16_f32 v240, v240, v241
	v_cvt_pk_bf16_f32 v241, v242, v243
	v_mov_b64_e32 v[248:249], v[226:227]
	s_add_i32 s0, s19, 112
	v_add_u32_e32 v253, s0, v0
	v_cmp_gt_i32_e32 vcc, s14, v253
	s_nop 1
	v_cndmask_b32_e32 v253, v168, v253, vcc
	v_mov_b64_e32 v[226:227], s[88:89]
	v_mad_i64_i32 v[226:227], s[0:1], v253, s15, v[226:227]
	v_mov_b32_e32 v244, v254
	v_mov_b32_e32 v245, 0
	v_lshl_add_u64 v[226:227], v[226:227], 0, v[244:245]
	global_load_dwordx2 v[150:151], v[226:227], off offset:0
	global_load_dwordx2 v[152:153], v[226:227], off offset:32
	global_load_dwordx2 v[154:155], v[226:227], off offset:64
	global_load_dwordx2 v[156:157], v[226:227], off offset:96
	v_ashrrev_i32_e32 v251, 31, v253
	v_mov_b32_e32 v250, v253
	v_lshlrev_b64 v[246:247], 11, v[250:251]
	v_lshl_add_u64 v[246:247], s[54:55], 0, v[246:247]
	v_lshl_add_u64 v[246:247], v[246:247], 0, v[244:245]
	global_load_dwordx2 v[158:159], v[246:247], off offset:0
	global_load_dwordx2 v[160:161], v[246:247], off offset:32
	global_load_dwordx2 v[162:163], v[246:247], off offset:64
	global_load_dwordx2 v[164:165], v[246:247], off offset:96
	v_lshlrev_b64 v[246:247], 6, v[250:251]
	v_lshl_add_u64 v[246:247], s[58:59], 0, v[246:247]
	v_lshl_add_u64 v[246:247], v[246:247], 0, s[20:21]
	global_load_dword v147, v[246:247], off
	s_add_i32 s0, s19, 80
	v_add_u32_e32 v253, s0, v0
	v_cmp_gt_i32_e32 vcc, s14, v253
	s_and_saveexec_b64 s[0:1], vcc
	global_store_dwordx2 v[248:249], v[228:229], off offset:0
	global_store_dwordx2 v[248:249], v[232:233], off offset:32
	global_store_dwordx2 v[248:249], v[236:237], off offset:64
	global_store_dwordx2 v[248:249], v[240:241], off offset:96
	s_or_b64 exec, exec, s[0:1]
	s_waitcnt vmcnt(9)
	v_lshlrev_b32_e32 v228, 16, v130
	v_and_b32_e32 v229, 0xffff0000, v130
	v_lshlrev_b32_e32 v230, 16, v131
	v_and_b32_e32 v231, 0xffff0000, v131
	v_lshlrev_b32_e32 v232, 16, v132
	v_and_b32_e32 v233, 0xffff0000, v132
	v_lshlrev_b32_e32 v234, 16, v133
	v_and_b32_e32 v235, 0xffff0000, v133
	v_lshlrev_b32_e32 v236, 16, v134
	v_and_b32_e32 v237, 0xffff0000, v134
	v_lshlrev_b32_e32 v238, 16, v135
	v_and_b32_e32 v239, 0xffff0000, v135
	v_lshlrev_b32_e32 v240, 16, v136
	v_and_b32_e32 v241, 0xffff0000, v136
	v_lshlrev_b32_e32 v242, 16, v137
	v_and_b32_e32 v243, 0xffff0000, v137
	v_add_f32_e32 v250, v228, v229
	v_add_f32_e32 v251, v230, v231
	v_add_f32_e32 v250, v250, v232
	v_add_f32_e32 v251, v251, v233
	v_add_f32_e32 v250, v250, v234
	v_add_f32_e32 v251, v251, v235
	v_add_f32_e32 v250, v250, v236
	v_add_f32_e32 v251, v251, v237
	v_add_f32_e32 v250, v250, v238
	v_add_f32_e32 v251, v251, v239
	v_add_f32_e32 v250, v250, v240
	v_add_f32_e32 v251, v251, v241
	v_add_f32_e32 v250, v250, v242
	v_add_f32_e32 v251, v251, v243
	v_add_f32_e32 v250, v250, v251
	ds_bpermute_b32 v251, v255, v250
	s_waitcnt lgkmcnt(0)
	v_add_f32_e32 v250, v250, v251
	ds_bpermute_b32 v251, v193, v250
	s_waitcnt lgkmcnt(0)
	v_add_f32_e32 v250, v250, v251
	v_fmac_f32_e32 v228, 0xbc800000, v250
	v_fmac_f32_e32 v229, 0xbc800000, v250
	v_fmac_f32_e32 v230, 0xbc800000, v250
	v_fmac_f32_e32 v231, 0xbc800000, v250
	v_fmac_f32_e32 v232, 0xbc800000, v250
	v_fmac_f32_e32 v233, 0xbc800000, v250
	v_fmac_f32_e32 v234, 0xbc800000, v250
	v_fmac_f32_e32 v235, 0xbc800000, v250
	v_fmac_f32_e32 v236, 0xbc800000, v250
	v_fmac_f32_e32 v237, 0xbc800000, v250
	v_fmac_f32_e32 v238, 0xbc800000, v250
	v_fmac_f32_e32 v239, 0xbc800000, v250
	v_fmac_f32_e32 v240, 0xbc800000, v250
	v_fmac_f32_e32 v241, 0xbc800000, v250
	v_fmac_f32_e32 v242, 0xbc800000, v250
	v_fmac_f32_e32 v243, 0xbc800000, v250
	v_mul_f32_e32 v250, v228, v228
	v_mul_f32_e32 v251, v229, v229
	v_fmac_f32_e32 v250, v230, v230
	v_fmac_f32_e32 v251, v231, v231
	v_fmac_f32_e32 v250, v232, v232
	v_fmac_f32_e32 v251, v233, v233
	v_fmac_f32_e32 v250, v234, v234
	v_fmac_f32_e32 v251, v235, v235
	v_fmac_f32_e32 v250, v236, v236
	v_fmac_f32_e32 v251, v237, v237
	v_fmac_f32_e32 v250, v238, v238
	v_fmac_f32_e32 v251, v239, v239
	v_fmac_f32_e32 v250, v240, v240
	v_fmac_f32_e32 v251, v241, v241
	v_fmac_f32_e32 v250, v242, v242
	v_fmac_f32_e32 v251, v243, v243
	v_add_f32_e32 v250, v250, v251
	ds_bpermute_b32 v251, v255, v250
	s_waitcnt lgkmcnt(0)
	v_add_f32_e32 v250, v250, v251
	ds_bpermute_b32 v251, v193, v250
	s_waitcnt lgkmcnt(0)
	v_add_f32_e32 v250, v250, v251
	v_fmamk_f32 v250, v250, 0x3c800000, v166
	v_mul_f32_e32 v251, 0x4b800000, v250
	v_cmp_gt_f32_e64 s[0:1], s16, v250
	s_nop 1
	v_cndmask_b32_e64 v250, v250, v251, s[0:1]
	v_rsq_f32_e32 v252, v250
	s_nop 0
	v_mul_f32_e32 v251, 0x45800000, v252
	v_cndmask_b32_e64 v252, v252, v251, s[0:1]
	v_mul_f32_e32 v228, v228, v252
	v_fma_f32 v228, v228, v194, v210
	v_lshlrev_b32_e32 v244, 16, v138
	v_fmac_f32_e32 v228, v146, v244
	v_mul_f32_e32 v228, v30, v228
	v_mul_f32_e32 v229, v229, v252
	v_fma_f32 v229, v229, v195, v211
	v_and_b32_e32 v244, 0xffff0000, v138
	v_fmac_f32_e32 v229, v146, v244
	v_mul_f32_e32 v229, v31, v229
	v_mul_f32_e32 v230, v230, v252
	v_fma_f32 v230, v230, v196, v212
	v_lshlrev_b32_e32 v244, 16, v139
	v_fmac_f32_e32 v230, v146, v244
	v_mul_f32_e32 v230, v32, v230
	v_mul_f32_e32 v231, v231, v252
	v_fma_f32 v231, v231, v197, v213
	v_and_b32_e32 v244, 0xffff0000, v139
	v_fmac_f32_e32 v231, v146, v244
	v_mul_f32_e32 v231, v33, v231
	v_cvt_pk_bf16_f32 v228, v228, v229
	v_cvt_pk_bf16_f32 v229, v230, v231
	v_mul_f32_e32 v232, v232, v252
	v_fma_f32 v232, v232, v198, v214
	v_lshlrev_b32_e32 v244, 16, v140
	v_fmac_f32_e32 v232, v146, v244
	v_mul_f32_e32 v232, v26, v232
	v_mul_f32_e32 v233, v233, v252
	v_fma_f32 v233, v233, v199, v215
	v_and_b32_e32 v244, 0xffff0000, v140
	v_fmac_f32_e32 v233, v146, v244
	v_mul_f32_e32 v233, v27, v233
	v_mul_f32_e32 v234, v234, v252
	v_fma_f32 v234, v234, v200, v216
	v_lshlrev_b32_e32 v244, 16, v141
	v_fmac_f32_e32 v234, v146, v244
	v_mul_f32_e32 v234, v28, v234
	v_mul_f32_e32 v235, v235, v252
	v_fma_f32 v235, v235, v201, v217
	v_and_b32_e32 v244, 0xffff0000, v141
	v_fmac_f32_e32 v235, v146, v244
	v_mul_f32_e32 v235, v29, v235
	v_cvt_pk_bf16_f32 v232, v232, v233
	v_cvt_pk_bf16_f32 v233, v234, v235
	v_mul_f32_e32 v236, v236, v252
	v_fma_f32 v236, v236, v202, v218
	v_lshlrev_b32_e32 v244, 16, v142
	v_fmac_f32_e32 v236, v146, v244
	v_mul_f32_e32 v236, v22, v236
	v_mul_f32_e32 v237, v237, v252
	v_fma_f32 v237, v237, v203, v219
	v_and_b32_e32 v244, 0xffff0000, v142
	v_fmac_f32_e32 v237, v146, v244
	v_mul_f32_e32 v237, v23, v237
	v_mul_f32_e32 v238, v238, v252
	v_fma_f32 v238, v238, v204, v220
	v_lshlrev_b32_e32 v244, 16, v143
	v_fmac_f32_e32 v238, v146, v244
	v_mul_f32_e32 v238, v24, v238
	v_mul_f32_e32 v239, v239, v252
	v_fma_f32 v239, v239, v205, v221
	v_and_b32_e32 v244, 0xffff0000, v143
	v_fmac_f32_e32 v239, v146, v244
	v_mul_f32_e32 v239, v25, v239
	v_cvt_pk_bf16_f32 v236, v236, v237
	v_cvt_pk_bf16_f32 v237, v238, v239
	v_mul_f32_e32 v240, v240, v252
	v_fma_f32 v240, v240, v206, v222
	v_lshlrev_b32_e32 v244, 16, v144
	v_fmac_f32_e32 v240, v146, v244
	v_mul_f32_e32 v240, v18, v240
	v_mul_f32_e32 v241, v241, v252
	v_fma_f32 v241, v241, v207, v223
	v_and_b32_e32 v244, 0xffff0000, v144
	v_fmac_f32_e32 v241, v146, v244
	v_mul_f32_e32 v241, v19, v241
	v_mul_f32_e32 v242, v242, v252
	v_fma_f32 v242, v242, v208, v224
	v_lshlrev_b32_e32 v244, 16, v145
	v_fmac_f32_e32 v242, v146, v244
	v_mul_f32_e32 v242, v20, v242
	v_mul_f32_e32 v243, v243, v252
	v_fma_f32 v243, v243, v209, v225
	v_and_b32_e32 v244, 0xffff0000, v145
	v_fmac_f32_e32 v243, v146, v244
	v_mul_f32_e32 v243, v21, v243
	v_cvt_pk_bf16_f32 v240, v240, v241
	v_cvt_pk_bf16_f32 v241, v242, v243
	s_add_i32 s0, s19, 96
	v_add_u32_e32 v253, s0, v0
	v_cmp_gt_i32_e32 vcc, s14, v253
	s_and_saveexec_b64 s[0:1], vcc
	global_store_dwordx2 v[148:149], v[228:229], off offset:0
	global_store_dwordx2 v[148:149], v[232:233], off offset:32
	global_store_dwordx2 v[148:149], v[236:237], off offset:64
	global_store_dwordx2 v[148:149], v[240:241], off offset:96
	s_or_b64 exec, exec, s[0:1]
	s_waitcnt vmcnt(0)
	v_lshlrev_b32_e32 v228, 16, v150
	v_and_b32_e32 v229, 0xffff0000, v150
	v_lshlrev_b32_e32 v230, 16, v151
	v_and_b32_e32 v231, 0xffff0000, v151
	v_lshlrev_b32_e32 v232, 16, v152
	v_and_b32_e32 v233, 0xffff0000, v152
	v_lshlrev_b32_e32 v234, 16, v153
	v_and_b32_e32 v235, 0xffff0000, v153
	v_lshlrev_b32_e32 v236, 16, v154
	v_and_b32_e32 v237, 0xffff0000, v154
	v_lshlrev_b32_e32 v238, 16, v155
	v_and_b32_e32 v239, 0xffff0000, v155
	v_lshlrev_b32_e32 v240, 16, v156
	v_and_b32_e32 v241, 0xffff0000, v156
	v_lshlrev_b32_e32 v242, 16, v157
	v_and_b32_e32 v243, 0xffff0000, v157
	v_add_f32_e32 v250, v228, v229
	v_add_f32_e32 v251, v230, v231
	v_add_f32_e32 v250, v250, v232
	v_add_f32_e32 v251, v251, v233
	v_add_f32_e32 v250, v250, v234
	v_add_f32_e32 v251, v251, v235
	v_add_f32_e32 v250, v250, v236
	v_add_f32_e32 v251, v251, v237
	v_add_f32_e32 v250, v250, v238
	v_add_f32_e32 v251, v251, v239
	v_add_f32_e32 v250, v250, v240
	v_add_f32_e32 v251, v251, v241
	v_add_f32_e32 v250, v250, v242
	v_add_f32_e32 v251, v251, v243
	v_add_f32_e32 v250, v250, v251
	ds_bpermute_b32 v251, v255, v250
	s_waitcnt lgkmcnt(0)
	v_add_f32_e32 v250, v250, v251
	ds_bpermute_b32 v251, v193, v250
	s_waitcnt lgkmcnt(0)
	v_add_f32_e32 v250, v250, v251
	v_fmac_f32_e32 v228, 0xbc800000, v250
	v_fmac_f32_e32 v229, 0xbc800000, v250
	v_fmac_f32_e32 v230, 0xbc800000, v250
	v_fmac_f32_e32 v231, 0xbc800000, v250
	v_fmac_f32_e32 v232, 0xbc800000, v250
	v_fmac_f32_e32 v233, 0xbc800000, v250
	v_fmac_f32_e32 v234, 0xbc800000, v250
	v_fmac_f32_e32 v235, 0xbc800000, v250
	v_fmac_f32_e32 v236, 0xbc800000, v250
	v_fmac_f32_e32 v237, 0xbc800000, v250
	v_fmac_f32_e32 v238, 0xbc800000, v250
	v_fmac_f32_e32 v239, 0xbc800000, v250
	v_fmac_f32_e32 v240, 0xbc800000, v250
	v_fmac_f32_e32 v241, 0xbc800000, v250
	v_fmac_f32_e32 v242, 0xbc800000, v250
	v_fmac_f32_e32 v243, 0xbc800000, v250
	v_mul_f32_e32 v250, v228, v228
	v_mul_f32_e32 v251, v229, v229
	v_fmac_f32_e32 v250, v230, v230
	v_fmac_f32_e32 v251, v231, v231
	v_fmac_f32_e32 v250, v232, v232
	v_fmac_f32_e32 v251, v233, v233
	v_fmac_f32_e32 v250, v234, v234
	v_fmac_f32_e32 v251, v235, v235
	v_fmac_f32_e32 v250, v236, v236
	v_fmac_f32_e32 v251, v237, v237
	v_fmac_f32_e32 v250, v238, v238
	v_fmac_f32_e32 v251, v239, v239
	v_fmac_f32_e32 v250, v240, v240
	v_fmac_f32_e32 v251, v241, v241
	v_fmac_f32_e32 v250, v242, v242
	v_fmac_f32_e32 v251, v243, v243
	v_add_f32_e32 v250, v250, v251
	ds_bpermute_b32 v251, v255, v250
	s_waitcnt lgkmcnt(0)
	v_add_f32_e32 v250, v250, v251
	ds_bpermute_b32 v251, v193, v250
	s_waitcnt lgkmcnt(0)
	v_add_f32_e32 v250, v250, v251
	v_fmamk_f32 v250, v250, 0x3c800000, v166
	v_mul_f32_e32 v251, 0x4b800000, v250
	v_cmp_gt_f32_e64 s[0:1], s16, v250
	s_nop 1
	v_cndmask_b32_e64 v250, v250, v251, s[0:1]
	v_rsq_f32_e32 v252, v250
	s_nop 0
	v_mul_f32_e32 v251, 0x45800000, v252
	v_cndmask_b32_e64 v252, v252, v251, s[0:1]
	v_mul_f32_e32 v228, v228, v252
	v_fma_f32 v228, v228, v194, v210
	v_lshlrev_b32_e32 v244, 16, v158
	v_fmac_f32_e32 v228, v147, v244
	v_mul_f32_e32 v228, v14, v228
	v_mul_f32_e32 v229, v229, v252
	v_fma_f32 v229, v229, v195, v211
	v_and_b32_e32 v244, 0xffff0000, v158
	v_fmac_f32_e32 v229, v147, v244
	v_mul_f32_e32 v229, v15, v229
	v_mul_f32_e32 v230, v230, v252
	v_fma_f32 v230, v230, v196, v212
	v_lshlrev_b32_e32 v244, 16, v159
	v_fmac_f32_e32 v230, v147, v244
	v_mul_f32_e32 v230, v16, v230
	v_mul_f32_e32 v231, v231, v252
	v_fma_f32 v231, v231, v197, v213
	v_and_b32_e32 v244, 0xffff0000, v159
	v_fmac_f32_e32 v231, v147, v244
	v_mul_f32_e32 v231, v17, v231
	v_cvt_pk_bf16_f32 v228, v228, v229
	v_cvt_pk_bf16_f32 v229, v230, v231
	v_mul_f32_e32 v232, v232, v252
	v_fma_f32 v232, v232, v198, v214
	v_lshlrev_b32_e32 v244, 16, v160
	v_fmac_f32_e32 v232, v147, v244
	v_mul_f32_e32 v232, v10, v232
	v_mul_f32_e32 v233, v233, v252
	v_fma_f32 v233, v233, v199, v215
	v_and_b32_e32 v244, 0xffff0000, v160
	v_fmac_f32_e32 v233, v147, v244
	v_mul_f32_e32 v233, v11, v233
	v_mul_f32_e32 v234, v234, v252
	v_fma_f32 v234, v234, v200, v216
	v_lshlrev_b32_e32 v244, 16, v161
	v_fmac_f32_e32 v234, v147, v244
	v_mul_f32_e32 v234, v12, v234
	v_mul_f32_e32 v235, v235, v252
	v_fma_f32 v235, v235, v201, v217
	v_and_b32_e32 v244, 0xffff0000, v161
	v_fmac_f32_e32 v235, v147, v244
	v_mul_f32_e32 v235, v13, v235
	v_cvt_pk_bf16_f32 v232, v232, v233
	v_cvt_pk_bf16_f32 v233, v234, v235
	v_mul_f32_e32 v236, v236, v252
	v_fma_f32 v236, v236, v202, v218
	v_lshlrev_b32_e32 v244, 16, v162
	v_fmac_f32_e32 v236, v147, v244
	v_mul_f32_e32 v236, v6, v236
	v_mul_f32_e32 v237, v237, v252
	v_fma_f32 v237, v237, v203, v219
	v_and_b32_e32 v244, 0xffff0000, v162
	v_fmac_f32_e32 v237, v147, v244
	v_mul_f32_e32 v237, v7, v237
	v_mul_f32_e32 v238, v238, v252
	v_fma_f32 v238, v238, v204, v220
	v_lshlrev_b32_e32 v244, 16, v163
	v_fmac_f32_e32 v238, v147, v244
	v_mul_f32_e32 v238, v8, v238
	v_mul_f32_e32 v239, v239, v252
	v_fma_f32 v239, v239, v205, v221
	v_and_b32_e32 v244, 0xffff0000, v163
	v_fmac_f32_e32 v239, v147, v244
	v_mul_f32_e32 v239, v9, v239
	v_cvt_pk_bf16_f32 v236, v236, v237
	v_cvt_pk_bf16_f32 v237, v238, v239
	v_mul_f32_e32 v240, v240, v252
	v_fma_f32 v240, v240, v206, v222
	v_lshlrev_b32_e32 v244, 16, v164
	v_fmac_f32_e32 v240, v147, v244
	v_mul_f32_e32 v240, v2, v240
	v_mul_f32_e32 v241, v241, v252
	v_fma_f32 v241, v241, v207, v223
	v_and_b32_e32 v244, 0xffff0000, v164
	v_fmac_f32_e32 v241, v147, v244
	v_mul_f32_e32 v241, v3, v241
	v_mul_f32_e32 v242, v242, v252
	v_fma_f32 v242, v242, v208, v224
	v_lshlrev_b32_e32 v244, 16, v165
	v_fmac_f32_e32 v242, v147, v244
	v_mul_f32_e32 v242, v4, v242
	v_mul_f32_e32 v243, v243, v252
	v_fma_f32 v243, v243, v209, v225
	v_and_b32_e32 v244, 0xffff0000, v165
	v_fmac_f32_e32 v243, v147, v244
	v_mul_f32_e32 v243, v5, v243
	v_cvt_pk_bf16_f32 v240, v240, v241
	v_cvt_pk_bf16_f32 v241, v242, v243
	s_add_i32 s0, s19, 112
	v_add_u32_e32 v253, s0, v0
	v_cmp_gt_i32_e32 vcc, s14, v253
	s_and_saveexec_b64 s[0:1], vcc
	global_store_dwordx2 v[226:227], v[228:229], off offset:0
	global_store_dwordx2 v[226:227], v[232:233], off offset:32
	global_store_dwordx2 v[226:227], v[236:237], off offset:64
	global_store_dwordx2 v[226:227], v[240:241], off offset:96
	s_or_b64 exec, exec, s[0:1]
	s_mov_b64 s[0:1], exec
	s_branch .LBB0_1246

	.amdhsa_kernel _Z4mega6Params
		.amdhsa_group_segment_fixed_size 0
		.amdhsa_private_segment_fixed_size 0
		.amdhsa_kernarg_size 568
		.amdhsa_user_sgpr_count 2
		.amdhsa_user_sgpr_dispatch_ptr 0
		.amdhsa_user_sgpr_queue_ptr 0
		.amdhsa_user_sgpr_kernarg_segment_ptr 1
		.amdhsa_user_sgpr_dispatch_id 0
		.amdhsa_user_sgpr_kernarg_preload_length 0
		.amdhsa_user_sgpr_kernarg_preload_offset 0
		.amdhsa_user_sgpr_private_segment_size 0
		.amdhsa_uses_dynamic_stack 0
		.amdhsa_enable_private_segment 0
		.amdhsa_system_sgpr_workgroup_id_x 1
		.amdhsa_system_sgpr_workgroup_id_y 0
		.amdhsa_system_sgpr_workgroup_id_z 0
		.amdhsa_system_sgpr_workgroup_info 0
		.amdhsa_system_vgpr_workitem_id 2
		.amdhsa_next_free_vgpr 256
		.amdhsa_next_free_sgpr 98
		.amdhsa_accum_offset 256
		.amdhsa_reserve_vcc 1
		.amdhsa_float_round_mode_32 0
		.amdhsa_float_round_mode_16_64 0
		.amdhsa_float_denorm_mode_32 3
		.amdhsa_float_denorm_mode_16_64 3
		.amdhsa_dx10_clamp 1
		.amdhsa_ieee_mode 1
		.amdhsa_fp16_overflow 0
		.amdhsa_tg_split 0
		.amdhsa_exception_fp_ieee_invalid_op 0
		.amdhsa_exception_fp_denorm_src 0
		.amdhsa_exception_fp_ieee_div_zero 0
		.amdhsa_exception_fp_ieee_overflow 0
		.amdhsa_exception_fp_ieee_underflow 0
		.amdhsa_exception_fp_ieee_inexact 0
		.amdhsa_exception_int_div_zero 0
	.end_amdhsa_kernel

.Lfunc_end0:
	.size	_Z4mega6Params, .Lfunc_end0-_Z4mega6Params
	.set _Z4mega6Params.num_vgpr, 256
	.set _Z4mega6Params.num_agpr, 0
	.set _Z4mega6Params.numbered_sgpr, 98
	.set _Z4mega6Params.num_named_barrier, 0
	.set _Z4mega6Params.private_seg_size, 0
	.set _Z4mega6Params.uses_vcc, 1
	.set _Z4mega6Params.uses_flat_scratch, 0
	.set _Z4mega6Params.has_dyn_sized_stack, 0
	.set _Z4mega6Params.has_recursion, 0
	.set _Z4mega6Params.has_indirect_call, 0

amdhsa.kernels:
  - .agpr_count:     0
    .args:
      - .offset:         0
        .size:           312
        .value_kind:     by_value
      - .offset:         312
        .size:           4
        .value_kind:     hidden_block_count_x
      - .offset:         316
        .size:           4
        .value_kind:     hidden_block_count_y
      - .offset:         320
        .size:           4
        .value_kind:     hidden_block_count_z
      - .offset:         324
        .size:           2
        .value_kind:     hidden_group_size_x
      - .offset:         326
        .size:           2
        .value_kind:     hidden_group_size_y
      - .offset:         328
        .size:           2
        .value_kind:     hidden_group_size_z
      - .offset:         330
        .size:           2
        .value_kind:     hidden_remainder_x
      - .offset:         332
        .size:           2
        .value_kind:     hidden_remainder_y
      - .offset:         334
        .size:           2
        .value_kind:     hidden_remainder_z
      - .offset:         352
        .size:           8
        .value_kind:     hidden_global_offset_x
      - .offset:         360
        .size:           8
        .value_kind:     hidden_global_offset_y
      - .offset:         368
        .size:           8
        .value_kind:     hidden_global_offset_z
      - .offset:         376
        .size:           2
        .value_kind:     hidden_grid_dims
      - .offset:         400
        .size:           8
        .value_kind:     hidden_multigrid_sync_arg
      - .offset:         432
        .size:           4
        .value_kind:     hidden_dynamic_lds_size
    .group_segment_fixed_size: 0
    .kernarg_segment_align: 8
    .kernarg_segment_size: 568
    .language:       OpenCL C
    .language_version:
      - 2
      - 0
    .max_flat_workgroup_size: 512
    .name:           _Z4mega6Params
    .private_segment_fixed_size: 0
    .sgpr_count:     104
    .sgpr_spill_count: 60
    .symbol:         _Z4mega6Params.kd
    .uniform_work_group_size: 1
    .uses_dynamic_stack: false
    .vgpr_count:     256
    .vgpr_spill_count: 0
    .wavefront_size: 64
